# MoBA: next-next-tile global loads issued one per PV MFMA group instead of inside the softmax section
# speedup vs baseline: 1.0033x; 1.0033x over previous
.LBB0_93:
	s_xor_b64 s[56:57], s[0:1], -1
	s_and_b64 s[0:1], s[0:1], exec
	s_cselect_b32 s8, s43, s44
	s_lshl_b32 s46, s8, 7
	s_ashr_i32 s1, s46, 31
	s_add_u32 s0, s46, s6
	s_addc_u32 s1, s1, 0
	v_lshl_add_u64 v[36:37], s[0:1], 0, v[116:117]
	v_mov_b64_e32 v[40:41], s[88:89]
	v_mad_u64_u32 v[38:39], s[10:11], v36, s72, v[40:41]
	v_mad_i32_i24 v39, v37, s72, v39
	s_lshl_b32 s20, s45, 1
	s_mov_b32 s77, 0
	v_mov_b64_e32 v[250:251], s[88:89]
	v_mad_u64_u32 v[250:251], s[82:83], v140, s72, v[250:251]
	v_mad_i32_i24 v251, v141, s72, v251
	v_lshl_add_u64 v[250:251], v[250:251], 0, s[20:21]
	v_lshl_add_u64 v[250:251], v[250:251], 0, v[2:3]
	v_lshl_add_u64 v[36:37], v[38:39], 0, s[20:21]
	v_lshl_add_u64 v[36:37], v[36:37], 0, v[2:3]
	v_add_co_u32_e32 v36, vcc, s3, v36
	s_nop 1
	v_addc_co_u32_e32 v37, vcc, 0, v37, vcc
	global_load_dwordx4 v[4:7], v[36:37], off
	v_lshl_add_u64 v[36:37], s[0:1], 0, v[122:123]
	v_mad_u64_u32 v[38:39], s[10:11], v36, s72, v[40:41]
	v_mad_i32_i24 v39, v37, s72, v39
	v_lshl_add_u64 v[36:37], v[38:39], 0, s[20:21]
	v_lshl_add_u64 v[36:37], v[36:37], 0, v[2:3]
	v_add_co_u32_e32 v36, vcc, s3, v36
	s_nop 1
	v_addc_co_u32_e32 v37, vcc, 0, v37, vcc
	global_load_dwordx4 v[8:11], v[36:37], off
	v_lshl_add_u64 v[36:37], s[0:1], 0, v[124:125]
	v_mad_u64_u32 v[38:39], s[10:11], v36, s72, v[40:41]
	v_mad_i32_i24 v39, v37, s72, v39
	v_lshl_add_u64 v[36:37], v[38:39], 0, s[20:21]
	v_lshl_add_u64 v[36:37], v[36:37], 0, v[2:3]
	v_add_co_u32_e32 v36, vcc, s3, v36
	s_nop 1
	v_addc_co_u32_e32 v37, vcc, 0, v37, vcc
	global_load_dwordx4 v[12:15], v[36:37], off
	v_lshl_add_u64 v[36:37], s[0:1], 0, v[126:127]
	v_mad_u64_u32 v[38:39], s[0:1], v36, s72, v[40:41]
	v_mad_i32_i24 v39, v37, s72, v39
	v_lshl_add_u64 v[36:37], v[38:39], 0, s[20:21]
	v_lshl_add_u64 v[36:37], v[36:37], 0, v[2:3]
	v_add_co_u32_e32 v36, vcc, 0x1000, v36
	s_nop 1
	v_addc_co_u32_e32 v37, vcc, 0, v37, vcc
	global_load_dwordx4 v[16:19], v[36:37], off
	v_lshrrev_b32_e32 v36, 5, v173
	v_lshlrev_b32_e32 v36, 9, v36
	v_mov_b32_e32 v37, 0
	v_lshl_add_u64 v[36:37], v[142:143], 0, v[36:37]
	global_load_dwordx4 v[20:23], v[36:37], off
	global_load_dwordx4 v[24:27], v[36:37], off offset:512
	s_barrier
	v_add_u32_e32 v52, v133, v170
	v_mov_b32_e32 v44, v156
	v_mov_b32_e32 v45, v135
	v_mov_b32_e32 v40, 0
	s_mov_b32 s0, 16
	v_mov_b32_e32 v41, v40
	v_mov_b32_e32 v42, v40
	v_mov_b32_e32 v43, v40
	s_waitcnt vmcnt(5)
	ds_write_b128 v52, v[4:7]
	s_waitcnt vmcnt(4)
	ds_write_b128 v188, v[8:11]
	s_waitcnt vmcnt(3)
	ds_write_b128 v189, v[12:15]
	s_waitcnt vmcnt(2)
	ds_write_b128 v190, v[16:19]
	s_waitcnt vmcnt(0)
	v_lshl_add_u32 v52, v173, 4, v171
	v_mov_b32_e32 v28, v20
	v_mov_b32_e32 v29, v24
	v_mov_b32_e32 v30, v21
	v_mov_b32_e32 v31, v25
	v_mov_b32_e32 v32, v22
	v_mov_b32_e32 v33, v26
	v_mov_b32_e32 v34, v23
	v_mov_b32_e32 v35, v27
	ds_write_b128 v52, v[28:31]
	ds_write_b128 v52, v[32:35] offset:16
	v_mov_b32_e32 v38, v40
	v_mov_b32_e32 v39, v40
	v_mov_b32_e32 v36, v40
	v_mov_b32_e32 v37, v40
	s_waitcnt lgkmcnt(0)
	s_barrier
	v_readfirstlane_b32 s82, v1
	s_ashr_i32 s83, s8, 1
	s_nop 3
	s_cmp_ge_i32 s82, s83
	s_cbranch_scc1 .Lgate_skip
	v_mov_b32_e32 v202, v45
	v_add_u32_e32 v203, 0x11000, v44
	ds_read_b128 v[4:7], v202
	ds_read_b128 v[8:11], v203
	ds_read_b128 v[12:15], v203 offset:16
	ds_read_b128 v[16:19], v203 offset:32
	ds_read_b128 v[20:23], v203 offset:48
	ds_read_b128 v[24:27], v203 offset:1024
	ds_read_b128 v[28:31], v203 offset:1040
	ds_read_b128 v[32:35], v203 offset:1056
	ds_read_b128 v[88:91], v203 offset:1072
	s_waitcnt lgkmcnt(7)
	ds_read_b128 v[92:95], v203 offset:2048
	ds_read_b128 v[96:99], v203 offset:2064
	ds_read_b128 v[100:103], v203 offset:2080
	ds_read_b128 v[104:107], v203 offset:2096
	ds_read_b128 v[108:111], v203 offset:3072
	ds_read_b128 v[112:115], v203 offset:3088
	ds_read_b128 v[194:197], v203 offset:3104
	ds_read_b128 v[198:201], v203 offset:3120

.Lms_inter:
	v_mov_b32_e32 v198, v197
	s_nop 1
	v_permlane16_swap_b32_e32 v197, v198
	v_max_f32_e32 v197, v197, v198
	v_mov_b32_e32 v198, v197
	s_nop 1
	v_permlane32_swap_b32_e32 v197, v198
	v_max3_f32 v197, v196, v197, v198
	v_cmp_neq_f32_e32 vcc, s73, v197
	s_nop 1
	v_cndmask_b32_e32 v198, 0, v197, vcc
	v_sub_f32_e32 v196, v196, v198
	v_mul_f32_e32 v199, 0x3e0293ee, v196
	v_mul_f32_e32 v196, 0xbe0293ee, v198
	v_cndmask_b32_e64 v198, v196, v215, s[0:1]
	v_fmamk_f32 v112, v112, 0x3e0293ee, v198
	v_exp_f32_e32 v112, v112
	s_xor_b32 s87, s15, 1
	v_fmamk_f32 v113, v113, 0x3e0293ee, v198
	v_exp_f32_e32 v113, v113
	s_mul_i32 s87, s87, 0x11000
	v_fmamk_f32 v114, v114, 0x3e0293ee, v198
	v_exp_f32_e32 v114, v114
	s_add_i32 s87, s87, 0
	v_fmamk_f32 v115, v115, 0x3e0293ee, v198
	v_exp_f32_e32 v115, v115
	v_add3_u32 v224, s87, v165, v216
	v_fmamk_f32 v108, v108, 0x3e0293ee, v198
	v_add3_u32 v223, s87, v0, v216
	v_add_f32_e32 v196, 0, v112
	v_exp_f32_e32 v108, v108
	v_add_u32_e32 v225, 0x8800, v224
	v_fmamk_f32 v109, v109, 0x3e0293ee, v198
	v_add_f32_e32 v196, v113, v196
	s_waitcnt vmcnt(7)
	v_exp_f32_e32 v109, v109
	v_fmamk_f32 v110, v110, 0x3e0293ee, v198
	ds_write_b128 v223, v[4:7]
	v_add_f32_e32 v196, v114, v196
	s_waitcnt vmcnt(6)
	v_exp_f32_e32 v110, v110
	v_fmamk_f32 v111, v111, 0x3e0293ee, v198
	ds_write2_b64 v225, v[8:9], v[10:11] offset1:2
	v_add_f32_e32 v196, v115, v196
	v_exp_f32_e32 v111, v111
	s_waitcnt vmcnt(5)
	v_fmamk_f32 v104, v104, 0x3e0293ee, v198
	v_add_f32_e32 v196, v108, v196
	ds_write_b128 v223, v[12:15] offset:8704
	v_exp_f32_e32 v104, v104
	v_add_u32_e32 v225, 0xa800, v224
	v_fmamk_f32 v105, v105, 0x3e0293ee, v198
	v_add_f32_e32 v196, v109, v196
	s_waitcnt vmcnt(4)
	v_exp_f32_e32 v105, v105
	v_fmamk_f32 v106, v106, 0x3e0293ee, v198
	ds_write2_b64 v225, v[16:17], v[18:19] offset0:64 offset1:66
	v_add_f32_e32 v196, v110, v196
	v_exp_f32_e32 v106, v106
	s_waitcnt vmcnt(3)
	v_fmamk_f32 v107, v107, 0x3e0293ee, v198
	ds_write_b128 v223, v[20:23] offset:17408
	v_add_f32_e32 v196, v111, v196
	v_exp_f32_e32 v107, v107
	v_add_u32_e32 v225, 0xc800, v224
	v_fmamk_f32 v100, v100, 0x3e0293ee, v198
	v_add_f32_e32 v196, v104, v196
	s_waitcnt vmcnt(2)
	v_exp_f32_e32 v100, v100
	v_fmamk_f32 v101, v101, 0x3e0293ee, v198
	ds_write2_b64 v225, v[24:25], v[26:27] offset0:128 offset1:130
	v_add_f32_e32 v196, v105, v196
	s_waitcnt vmcnt(1)
	v_exp_f32_e32 v101, v101
	v_fmamk_f32 v102, v102, 0x3e0293ee, v198
	ds_write_b128 v223, v[28:31] offset:26112
	v_add_f32_e32 v196, v106, v196
	v_exp_f32_e32 v102, v102
	v_add_u32_e32 v223, 0xe800, v224
	v_fmamk_f32 v103, v103, 0x3e0293ee, v198
	v_add_f32_e32 v196, v107, v196
	s_waitcnt vmcnt(0)
	v_exp_f32_e32 v103, v103
	ds_write2_b64 v223, v[32:33], v[34:35] offset0:192 offset1:194
	s_andn2_b64 vcc, exec, s[80:81]
	s_cbranch_vccnz .Lms_t2plain
	v_fmamk_f32 v96, v96, 0x3e0293ee, v198
	v_add_f32_e32 v196, v100, v196
	v_exp_f32_e32 v96, v96
	s_lshr_b32 s82, s14, 1
	v_fmamk_f32 v97, v97, 0x3e0293ee, v198
	v_add_f32_e32 v196, v101, v196
	s_sub_i32 s82, s47, s82
	v_exp_f32_e32 v97, v97
	v_fmamk_f32 v98, v98, 0x3e0293ee, v198
	s_lshl_b32 s83, s14, 7
	v_add_f32_e32 v196, v102, v196
	v_exp_f32_e32 v98, v98
	v_fmamk_f32 v99, v99, 0x3e0293ee, v198
	s_lshl_b32 s82, s82, 8
	v_add_f32_e32 v196, v103, v196
	v_exp_f32_e32 v99, v99
	s_and_b32 s83, s83, 0x80
	v_fmamk_f32 v92, v92, 0x3e0293ee, v198
	v_add_f32_e32 v196, v96, v196
	s_or_b32 s82, s82, s83
	v_exp_f32_e32 v92, v92
	v_fmamk_f32 v93, v93, 0x3e0293ee, v198
	s_ashr_i32 s83, s82, 31
	v_add_f32_e32 v196, v97, v196
	v_exp_f32_e32 v93, v93
	v_fmamk_f32 v94, v94, 0x3e0293ee, v198
	v_lshl_add_u64 v[28:29], s[82:83], 1, v[118:119]
	v_add_f32_e32 v196, v98, v196
	v_exp_f32_e32 v94, v94
	s_mul_i32 s82, s82, s72
	v_fmamk_f32 v95, v95, 0x3e0293ee, v198
	v_add_f32_e32 v196, v99, v196
	s_add_u32 s82, s82, s3
	v_exp_f32_e32 v95, v95
	v_fmamk_f32 v88, v88, 0x3e0293ee, v198
	s_mov_b32 s83, 0
	v_add_f32_e32 v196, v92, v196
	v_exp_f32_e32 v88, v88
	v_fmamk_f32 v89, v89, 0x3e0293ee, v198
	v_lshl_add_u64 v[4:5], v[250:251], 0, s[82:83]
	v_add_f32_e32 v196, v93, v196
	v_exp_f32_e32 v89, v89
	v_lshl_add_u64 v[8:9], v[28:29], 0, v[146:147]
	v_fmamk_f32 v90, v90, 0x3e0293ee, v198
	v_add_f32_e32 v196, v94, v196
	s_add_u32 s82, s82, 0x3c000
	v_exp_f32_e32 v90, v90
	v_fmamk_f32 v91, v91, 0x3e0293ee, v198
	v_lshl_add_u64 v[12:13], v[250:251], 0, s[82:83]
	v_add_f32_e32 v196, v95, v196
	v_exp_f32_e32 v91, v91
	v_add_f32_e32 v196, v88, v196
	v_lshl_add_u64 v[16:17], v[28:29], 0, v[148:149]
	v_add_f32_e32 v196, v89, v196
	v_add_f32_e32 v196, v90, v196
	s_add_u32 s82, s82, 0x3c000
	v_fmamk_f32 v84, v84, 0x3e0293ee, v198
	v_add_f32_e32 v200, v91, v196
	v_lshl_add_u64 v[20:21], v[250:251], 0, s[82:83]
	v_exp_f32_e32 v196, v84
	v_fmamk_f32 v85, v85, 0x3e0293ee, v198
	v_lshl_add_u64 v[24:25], v[28:29], 0, v[150:151]
	v_exp_f32_e32 v85, v85
	v_fmamk_f32 v86, v86, 0x3e0293ee, v198
	v_exp_f32_e32 v86, v86
	s_add_u32 s82, s82, 0x3c000
	v_fmac_f32_e32 v198, 0x3e0293ee, v87
	v_exp_f32_e32 v87, v198
	v_lshl_add_u64 v[30:31], v[250:251], 0, s[82:83]
	v_add_f32_e32 v84, v196, v200
	v_add_f32_e32 v84, v85, v84
	v_lshl_add_u64 v[32:33], v[28:29], 0, v[152:153]
	v_add_f32_e32 v84, v86, v84
	v_add_f32_e32 v198, v87, v84
	s_mov_b32 s77, 1
	s_branch .Lms_join

.LBB0_158:
	s_cmp_eq_u32 s77, 0
	s_cbranch_scc1 .Lpv_plain
	s_mov_b32 s77, 0
	s_waitcnt lgkmcnt(0)
	v_add_f32_e32 v198, v198, v199
	v_fmac_f32_e32 v198, v194, v84
	v_cvt_pk_bf16_f32 v112, v112, v113
	v_cvt_pk_bf16_f32 v113, v114, v115
	v_cvt_pk_bf16_f32 v114, v108, v109
	v_cvt_pk_bf16_f32 v115, v110, v111
	v_cvt_pk_bf16_f32 v104, v104, v105
	v_cvt_pk_bf16_f32 v105, v106, v107
	v_cvt_pk_bf16_f32 v106, v100, v101
	v_cvt_pk_bf16_f32 v107, v102, v103
	v_cvt_pk_bf16_f32 v96, v96, v97
	v_cvt_pk_bf16_f32 v97, v98, v99
	v_cvt_pk_bf16_f32 v98, v92, v93
	v_cvt_pk_bf16_f32 v99, v94, v95
	v_cvt_pk_bf16_f32 v88, v88, v89
	v_cvt_pk_bf16_f32 v89, v90, v91
	v_cvt_pk_bf16_f32 v90, v196, v85
	v_cvt_pk_bf16_f32 v91, v86, v87
	ds_read_b128 v[84:87], v195 offset:52224
	ds_read_b128 v[92:95], v195 offset:52496
	ds_read_b128 v[100:103], v195 offset:60928
	ds_read_b128 v[108:111], v195 offset:61200
	s_waitcnt lgkmcnt(4)
	v_mfma_f32_16x16x32_bf16 v[80:83], v[202:205], v[112:115], v[80:83]
	v_mfma_f32_16x16x32_bf16 v[76:79], v[206:209], v[112:115], v[76:79]
	v_mfma_f32_16x16x32_bf16 v[72:75], v[230:233], v[112:115], v[72:75]
	v_mfma_f32_16x16x32_bf16 v[68:71], v[234:237], v[112:115], v[68:71]
	global_load_dwordx4 v[4:7], v[4:5], off offset:1024
	ds_read_b128 v[202:205], v195 offset:34880
	ds_read_b128 v[206:209], v195 offset:35152
	ds_read_b128 v[230:233], v195 offset:43584
	ds_read_b128 v[234:237], v195 offset:43856
	s_waitcnt lgkmcnt(4)
	v_mfma_f32_16x16x32_bf16 v[64:67], v[84:87], v[112:115], v[64:67]
	v_mfma_f32_16x16x32_bf16 v[60:63], v[92:95], v[112:115], v[60:63]
	v_mfma_f32_16x16x32_bf16 v[56:59], v[100:103], v[112:115], v[56:59]
	v_mfma_f32_16x16x32_bf16 v[52:55], v[108:111], v[112:115], v[52:55]
	global_load_dwordx4 v[8:11], v[8:9], off
	ds_read_b128 v[84:87], v195 offset:52288
	ds_read_b128 v[92:95], v195 offset:52560
	ds_read_b128 v[100:103], v195 offset:60992
	ds_read_b128 v[108:111], v195 offset:61264
	s_waitcnt lgkmcnt(4)
	v_mfma_f32_16x16x32_bf16 v[80:83], v[202:205], v[104:107], v[80:83]
	v_mfma_f32_16x16x32_bf16 v[76:79], v[206:209], v[104:107], v[76:79]
	v_mfma_f32_16x16x32_bf16 v[72:75], v[230:233], v[104:107], v[72:75]
	v_mfma_f32_16x16x32_bf16 v[68:71], v[234:237], v[104:107], v[68:71]
	global_load_dwordx4 v[12:15], v[12:13], off offset:1024
	ds_read_b128 v[202:205], v195 offset:34944
	ds_read_b128 v[206:209], v195 offset:35216
	ds_read_b128 v[230:233], v195 offset:43648
	ds_read_b128 v[234:237], v195 offset:43920
	s_waitcnt lgkmcnt(4)
	v_mfma_f32_16x16x32_bf16 v[64:67], v[84:87], v[104:107], v[64:67]
	v_mfma_f32_16x16x32_bf16 v[60:63], v[92:95], v[104:107], v[60:63]
	v_mfma_f32_16x16x32_bf16 v[56:59], v[100:103], v[104:107], v[56:59]
	v_mfma_f32_16x16x32_bf16 v[52:55], v[108:111], v[104:107], v[52:55]
	global_load_dwordx4 v[16:19], v[16:17], off
	ds_read_b128 v[84:87], v195 offset:52352
	ds_read_b128 v[92:95], v195 offset:52624
	ds_read_b128 v[100:103], v195 offset:61056
	ds_read_b128 v[108:111], v195 offset:61328
	s_waitcnt lgkmcnt(4)
	v_mfma_f32_16x16x32_bf16 v[80:83], v[202:205], v[96:99], v[80:83]
	v_mfma_f32_16x16x32_bf16 v[76:79], v[206:209], v[96:99], v[76:79]
	v_mfma_f32_16x16x32_bf16 v[72:75], v[230:233], v[96:99], v[72:75]
	v_mfma_f32_16x16x32_bf16 v[68:71], v[234:237], v[96:99], v[68:71]
	global_load_dwordx4 v[20:23], v[20:21], off offset:1024
	ds_read_b128 v[202:205], v195 offset:35008
	ds_read_b128 v[206:209], v195 offset:35280
	ds_read_b128 v[230:233], v195 offset:43712
	ds_read_b128 v[234:237], v195 offset:43984
	s_waitcnt lgkmcnt(4)
	v_mfma_f32_16x16x32_bf16 v[64:67], v[84:87], v[96:99], v[64:67]
	v_mfma_f32_16x16x32_bf16 v[60:63], v[92:95], v[96:99], v[60:63]
	v_mfma_f32_16x16x32_bf16 v[56:59], v[100:103], v[96:99], v[56:59]
	v_mfma_f32_16x16x32_bf16 v[52:55], v[108:111], v[96:99], v[52:55]
	global_load_dwordx4 v[24:27], v[24:25], off
	ds_read_b128 v[84:87], v195 offset:52416
	ds_read_b128 v[92:95], v195 offset:52688
	ds_read_b128 v[100:103], v195 offset:61120
	ds_read_b128 v[108:111], v195 offset:61392
	s_waitcnt lgkmcnt(4)
	v_mfma_f32_16x16x32_bf16 v[80:83], v[202:205], v[88:91], v[80:83]
	v_mfma_f32_16x16x32_bf16 v[76:79], v[206:209], v[88:91], v[76:79]
	v_mfma_f32_16x16x32_bf16 v[72:75], v[230:233], v[88:91], v[72:75]
	v_mfma_f32_16x16x32_bf16 v[68:71], v[234:237], v[88:91], v[68:71]
	global_load_dwordx4 v[28:31], v[30:31], off offset:1024
	s_waitcnt lgkmcnt(0)
	v_mfma_f32_16x16x32_bf16 v[64:67], v[84:87], v[88:91], v[64:67]
	v_mfma_f32_16x16x32_bf16 v[60:63], v[92:95], v[88:91], v[60:63]
	v_mfma_f32_16x16x32_bf16 v[56:59], v[100:103], v[88:91], v[56:59]
	v_mfma_f32_16x16x32_bf16 v[52:55], v[108:111], v[88:91], v[52:55]
	global_load_dwordx4 v[32:35], v[32:33], off
	v_mov_b32_e32 v194, v198
	s_andn2_b64 vcc, exec, s[8:9]
	s_xor_b32 s15, s15, 1
	s_cbranch_vccnz .LBB0_138
	s_branch .LBB0_92
